# E2+E3 of the chunked scan fused into wave 0 on f32-operand MFMA (v_mfma_f32_16x16x4_f32, two chained products, first kept in accumulators): 1 block barrier instead of 3 per chunk
# speedup vs baseline: 1.1194x; 1.0090x over previous
.LBB0_1034:
	s_or_b64 exec, exec, s[36:37]
	s_cmp_lg_u64 s[30:31], 0
	s_cbranch_scc1 .Le23_skip_a
	v_and_b32_e32 v33, 15, v113
	v_lshrrev_b32_e32 v35, 4, v113
	v_mul_u32_u24_e32 v36, 0x84, v35
	v_mul_u32_u24_e32 v37, 0x44, v33
	v_mul_u32_u24_e32 v38, 0x110, v35
	v_lshl_add_u32 v36, v33, 2, v36
	v_lshl_add_u32 v37, v35, 2, v37
	v_lshl_add_u32 v38, v33, 2, v38
	ds_read_b32 v40, v36 offset:8384
	ds_read_b32 v44, v37 offset:12544
	ds_read_b32 v41, v36 offset:8912
	ds_read_b32 v45, v37 offset:12560
	ds_read_b32 v42, v36 offset:9440
	ds_read_b32 v46, v37 offset:12576
	ds_read_b32 v43, v36 offset:9968
	ds_read_b32 v47, v37 offset:12592
	ds_read_b32 v214, v38 offset:13632
	ds_read_b32 v215, v38 offset:13700
	ds_read_b32 v216, v38 offset:13768
	ds_read_b32 v217, v38 offset:13836
	v_mul_u32_u24_e32 v88, 0x50, v33
	v_lshl_add_u32 v88, v35, 3, v88
	v_lshrrev_b32_e32 v39, 2, v113
	v_mul_u32_u24_e32 v39, 0x50, v39
	v_and_b32_e32 v33, 3, v113
	v_lshl_add_u32 v39, v33, 3, v39
	v_mov_b32_e32 v230, 0
	v_mov_b32_e32 v231, 0
	ds_write_b64 v39, v[230:231] offset:58336
	s_waitcnt lgkmcnt(11)
	v_mfma_f32_16x16x4_f32 v[220:223], v40, v44, 0
	s_waitcnt lgkmcnt(9)
	v_mfma_f32_16x16x4_f32 v[220:223], v41, v45, v[220:223]
	s_waitcnt lgkmcnt(7)
	v_mfma_f32_16x16x4_f32 v[220:223], v42, v46, v[220:223]
	s_waitcnt lgkmcnt(5)
	v_mfma_f32_16x16x4_f32 v[220:223], v43, v47, v[220:223]
	s_waitcnt lgkmcnt(1)
	s_nop 9
	v_mfma_f32_16x16x4_f32 v[224:227], v220, v214, 0
	v_mfma_f32_16x16x4_f32 v[224:227], v221, v215, v[224:227]
	v_mfma_f32_16x16x4_f32 v[224:227], v222, v216, v[224:227]
	v_mfma_f32_16x16x4_f32 v[224:227], v223, v217, v[224:227]
	s_nop 9
	v_cvt_pk_bf16_f32 v228, v224, v225
	v_cvt_pk_bf16_f32 v229, v226, v227
	ds_write_b64 v88, v[228:229] offset:59584
.Le23_skip_a:
	v_lshlrev_b32_e32 v101, 3, v115
	v_mul_u32_u24_e32 v115, 0x90, v112
	v_or_b32_e32 v34, v115, v101
	s_waitcnt lgkmcnt(0)
	s_barrier
	v_add_u32_e32 v100, 0x4000, v34
	ds_read2_b64 v[36:39], v100 offset0:32 offset1:34
	v_cvt_pk_bf16_f32 v32, v0, v1
	v_cvt_pk_bf16_f32 v33, v2, v3
	v_cvt_pk_bf16_f32 v34, v4, v5
	v_cvt_pk_bf16_f32 v35, v6, v7
	ds_read2_b64 v[116:119], v100 offset0:36 offset1:38
	v_cvt_pk_bf16_f32 v88, v8, v9
	s_waitcnt lgkmcnt(1)
	v_mfma_f32_32x32x16_bf16 v[32:47], v[36:39], v[32:35], 0
	v_cvt_pk_bf16_f32 v89, v10, v11
	v_cvt_pk_bf16_f32 v90, v12, v13
	v_cvt_pk_bf16_f32 v91, v14, v15
	ds_read2_b64 v[124:127], v100 offset0:40 offset1:42
	v_cvt_pk_bf16_f32 v92, v16, v17
	v_cvt_pk_bf16_f32 v93, v18, v19
	v_cvt_pk_bf16_f32 v94, v20, v21
	s_waitcnt lgkmcnt(1)
	v_mfma_f32_32x32x16_bf16 v[32:47], v[116:119], v[88:91], v[32:47]
	v_cvt_pk_bf16_f32 v95, v22, v23
	ds_read2_b64 v[116:119], v100 offset0:44 offset1:46
	v_cvt_pk_bf16_f32 v120, v24, v25
	v_cvt_pk_bf16_f32 v121, v26, v27
	v_cvt_pk_bf16_f32 v122, v28, v29
	v_cvt_pk_bf16_f32 v123, v30, v31
	v_and_b32_e32 v96, 24, v113
	s_waitcnt lgkmcnt(1)
	v_mfma_f32_32x32x16_bf16 v[32:47], v[124:127], v[92:95], v[32:47]
	v_mov_b32_e32 v88, s44
	v_bitop3_b32 v99, v101, v113, 24 bitop3:0x78
	v_mad_u32_u24 v88, v114, s51, v88
	v_bitop3_b32 v100, v101, v96, 16 bitop3:0x36
	v_lshl_add_u32 v89, v99, 1, v88
	v_lshl_add_u32 v88, v100, 1, v88
	ds_read_b128 v[92:95], v89 offset:45440
	ds_read_b128 v[88:91], v88 offset:45440
	s_waitcnt lgkmcnt(2)
	v_mfma_f32_32x32x16_bf16 v[32:47], v[116:119], v[120:123], v[32:47]
	v_cndmask_b32_e64 v113, 0, 1, s[18:19]
	v_cmp_ne_u32_e64 s[10:11], 1, v113
	s_andn2_b64 vcc, exec, s[18:19]
	s_cbranch_vccnz .LBB0_1036
	v_lshlrev_b32_e32 v113, 6, v112
	v_sub_u32_e32 v113, v115, v113
	v_lshl_add_u32 v101, v101, 1, v113
	ds_read_b128 v[114:117], v101 offset:50624
	ds_read_b128 v[118:121], v101 offset:50656
	s_waitcnt lgkmcnt(1)
	v_mfma_f32_32x32x16_bf16 v[32:47], v[114:117], v[92:95], v[32:47]
	s_waitcnt lgkmcnt(0)
	v_mfma_f32_32x32x16_bf16 v[32:47], v[118:121], v[88:91], v[32:47]

.LBB0_1213:
	s_or_b64 exec, exec, s[58:59]
	s_cmp_lg_u64 s[54:55], 0
	s_cbranch_scc1 .Le23_skip_b
	v_and_b32_e32 v34, 15, v141
	v_lshrrev_b32_e32 v35, 4, v141
	v_mul_u32_u24_e32 v36, 0x84, v35
	v_mul_u32_u24_e32 v37, 0x44, v34
	v_mul_u32_u24_e32 v38, 0x110, v35
	v_lshl_add_u32 v36, v34, 2, v36
	v_lshl_add_u32 v37, v35, 2, v37
	v_lshl_add_u32 v38, v34, 2, v38
	ds_read_b32 v40, v36 offset:8384
	ds_read_b32 v44, v37 offset:12544
	ds_read_b32 v41, v36 offset:8912
	ds_read_b32 v45, v37 offset:12560
	ds_read_b32 v42, v36 offset:9440
	ds_read_b32 v46, v37 offset:12576
	ds_read_b32 v43, v36 offset:9968
	ds_read_b32 v47, v37 offset:12592
	ds_read_b32 v214, v38 offset:13632
	ds_read_b32 v215, v38 offset:13700
	ds_read_b32 v216, v38 offset:13768
	ds_read_b32 v217, v38 offset:13836
	v_mul_u32_u24_e32 v48, 0x50, v34
	v_lshl_add_u32 v48, v35, 3, v48
	v_lshrrev_b32_e32 v39, 2, v141
	v_mul_u32_u24_e32 v39, 0x50, v39
	v_and_b32_e32 v34, 3, v141
	v_lshl_add_u32 v39, v34, 3, v39
	v_mov_b32_e32 v230, 0
	v_mov_b32_e32 v231, 0
	ds_write_b64 v39, v[230:231] offset:58336
	s_waitcnt lgkmcnt(11)
	v_mfma_f32_16x16x4_f32 v[220:223], v40, v44, 0
	s_waitcnt lgkmcnt(9)
	v_mfma_f32_16x16x4_f32 v[220:223], v41, v45, v[220:223]
	s_waitcnt lgkmcnt(7)
	v_mfma_f32_16x16x4_f32 v[220:223], v42, v46, v[220:223]
	s_waitcnt lgkmcnt(5)
	v_mfma_f32_16x16x4_f32 v[220:223], v43, v47, v[220:223]
	s_waitcnt lgkmcnt(1)
	s_nop 9
	v_mfma_f32_16x16x4_f32 v[224:227], v220, v214, 0
	v_mfma_f32_16x16x4_f32 v[224:227], v221, v215, v[224:227]
	v_mfma_f32_16x16x4_f32 v[224:227], v222, v216, v[224:227]
	v_mfma_f32_16x16x4_f32 v[224:227], v223, v217, v[224:227]
	s_nop 9
	v_cvt_pk_bf16_f32 v228, v224, v225
	v_cvt_pk_bf16_f32 v229, v226, v227
	ds_write_b64 v48, v[228:229] offset:59584
.Le23_skip_b:
	s_waitcnt lgkmcnt(0)
	s_barrier
	s_andn2_b64 vcc, exec, s[8:9]
	s_cbranch_vccnz .LBB0_1106
	v_lshlrev_b32_e32 v80, 1, v0
	v_add_u32_e32 v46, v66, v80
	v_add_u32_e32 v47, 0x4000, v46
	ds_read2_b64 v[34:37], v47 offset0:32 offset1:34
	v_cvt_pk_bf16_f32 v38, v18, v19
	v_cvt_pk_bf16_f32 v39, v20, v21
	v_cvt_pk_bf16_f32 v40, v22, v23
	v_cvt_pk_bf16_f32 v41, v24, v25
	ds_read2_b64 v[42:45], v47 offset0:36 offset1:38
	v_lshlrev_b32_e32 v48, 3, v51
	v_cvt_pk_bf16_f32 v72, v26, v27
	v_cvt_pk_bf16_f32 v73, v28, v29
	s_waitcnt lgkmcnt(1)
	v_mfma_f32_32x32x16_bf16 v[50:65], v[34:37], v[38:41], 0
	v_cvt_pk_bf16_f32 v74, v30, v31
	v_cvt_pk_bf16_f32 v75, v32, v33
	ds_read2_b64 v[34:37], v47 offset0:40 offset1:42
	v_cvt_pk_bf16_f32 v76, v2, v3
	v_cvt_pk_bf16_f32 v77, v4, v5
	v_cvt_pk_bf16_f32 v78, v6, v7
	v_cvt_pk_bf16_f32 v79, v8, v9
	s_waitcnt lgkmcnt(1)
	v_mfma_f32_32x32x16_bf16 v[50:65], v[42:45], v[72:75], v[50:65]
	ds_read2_b64 v[42:45], v47 offset0:44 offset1:46
	v_cvt_pk_bf16_f32 v172, v10, v11
	v_cvt_pk_bf16_f32 v173, v12, v13
	v_cvt_pk_bf16_f32 v174, v14, v15
	v_cvt_pk_bf16_f32 v175, v16, v17
	v_mov_b32_e32 v49, s92
	v_bitop3_b32 v47, v48, v141, 24 bitop3:0x78
	s_waitcnt lgkmcnt(1)
	v_mfma_f32_32x32x16_bf16 v[50:65], v[34:37], v[76:79], v[50:65]
	v_lshlrev_b32_e32 v34, 6, v70
	v_sub_u32_e32 v177, v66, v34
	v_lshl_add_u32 v70, v48, 1, v177
	ds_read_b128 v[34:37], v70 offset:50624
	v_mad_u32_u24 v49, v71, s77, v49
	v_lshlrev_b32_e32 v207, 1, v47
	v_and_b32_e32 v145, 24, v141
	s_waitcnt lgkmcnt(1)
	v_mfma_f32_32x32x16_bf16 v[50:65], v[42:45], v[172:175], v[50:65]
	v_add_u32_e32 v42, v49, v207
	ds_read_b128 v[130:133], v42 offset:45440
	v_bitop3_b32 v67, v48, v145, 16 bitop3:0x36
	v_lshlrev_b32_e32 v212, 1, v67
	v_add_u32_e32 v71, 0x5000, v46
	v_add_u32_e32 v47, v49, v212
	ds_read_b128 v[42:45], v70 offset:50656
	ds_read_b128 v[126:129], v47 offset:45440
	s_waitcnt lgkmcnt(2)
	v_mfma_f32_32x32x16_bf16 v[50:65], v[34:37], v[130:133], v[50:65]
	ds_read2_b64 v[34:37], v71 offset0:96 offset1:98
	ds_read2_b64 v[66:69], v71 offset0:100 offset1:102
	ds_read2_b64 v[178:181], v71 offset0:104 offset1:106
	ds_read2_b64 v[182:185], v71 offset0:108 offset1:110
	ds_read_b128 v[186:189], v70 offset:55744
	ds_read_b128 v[190:193], v70 offset:55776
	v_lshlrev_b32_e32 v81, 2, v0
	s_sub_i32 s58, s93, 32
	s_add_i32 s59, s94, 32
	s_and_b64 s[12:13], s[10:11], exec
	s_waitcnt lgkmcnt(6)
	v_mfma_f32_32x32x16_bf16 v[50:65], v[42:45], v[126:129], v[50:65]
	s_cselect_b32 s12, s58, s59
	s_add_i32 s12, s12, s87
	s_waitcnt lgkmcnt(5)
	v_mfma_f32_32x32x16_bf16 v[34:49], v[34:37], v[38:41], 0
	s_nop 7
	v_cvt_pk_bf16_f32 v50, v50, v51
	v_cvt_pk_bf16_f32 v51, v52, v53
	v_cvt_pk_bf16_f32 v52, v54, v55
	v_cvt_pk_bf16_f32 v53, v56, v57
	s_waitcnt lgkmcnt(4)
	v_mfma_f32_32x32x16_bf16 v[34:49], v[66:69], v[72:75], v[34:49]
	ds_read_b128 v[66:69], v81 offset:60928
	ds_read_b128 v[70:73], v81 offset:60960
	ds_read_b128 v[194:197], v81 offset:60864
	ds_read_b128 v[198:201], v81 offset:60896
	ds_read_b128 v[202:205], v81 offset:60992
	ds_read_b128 v[208:211], v81 offset:61024
	s_waitcnt lgkmcnt(4)
	v_pk_mul_f32 v[30:31], v[30:31], v[70:71]
	v_pk_mul_f32 v[26:27], v[26:27], v[66:67]
	v_pk_mul_f32 v[32:33], v[32:33], v[72:73]
	v_pk_mul_f32 v[28:29], v[28:29], v[68:69]
	ds_read_b128 v[66:69], v81 offset:61056
	ds_read_b128 v[70:73], v81 offset:61088
	s_waitcnt lgkmcnt(4)
	v_pk_mul_f32 v[22:23], v[22:23], v[198:199]
	v_mfma_f32_32x32x16_bf16 v[34:49], v[178:181], v[76:79], v[34:49]
	v_mul_f32_e64 v24, v24, v200
	v_mul_f32_e64 v25, v25, v201
	s_waitcnt lgkmcnt(1)
	v_mul_f32_e64 v10, v10, v66
	v_mul_f32_e64 v11, v11, v67
	s_waitcnt lgkmcnt(0)
	v_pk_mul_f32 v[14:15], v[14:15], v[70:71]
	v_pk_mul_f32 v[16:17], v[16:17], v[72:73]
	v_pk_mul_f32 v[12:13], v[12:13], v[68:69]
	v_pk_mul_f32 v[20:21], v[20:21], v[196:197]
	v_pk_mul_f32 v[18:19], v[18:19], v[194:195]
	v_mfma_f32_32x32x16_bf16 v[34:49], v[182:185], v[172:175], v[34:49]
	v_add_u32_e32 v172, v177, v80
	v_add_u32_e32 v66, 0xe000, v172
	ds_read2_b64 v[74:77], v66 offset0:120 offset1:122
	ds_read2_b64 v[54:57], v66 offset0:124 offset1:126
	v_mul_f32_e64 v6, v6, v208
	v_mul_f32_e64 v7, v7, v209
	v_pk_mul_f32 v[8:9], v[8:9], v[210:211]
	v_pk_mul_f32 v[4:5], v[4:5], v[204:205]
	s_waitcnt lgkmcnt(1)
	v_mfma_f32_32x32x16_bf16 v[66:81], v[74:77], v[50:53], 0
	v_cvt_pk_bf16_f32 v50, v58, v59
	v_cvt_pk_bf16_f32 v51, v60, v61
	v_cvt_pk_bf16_f32 v52, v62, v63
	v_cvt_pk_bf16_f32 v53, v64, v65
	v_add_u32_e32 v62, v177, v212
	v_pk_mul_f32 v[2:3], v[2:3], v[202:203]
	s_waitcnt lgkmcnt(0)
	v_mfma_f32_32x32x16_bf16 v[66:81], v[54:57], v[50:53], v[66:81]
	v_add_u32_e32 v54, v177, v207
	ds_read_b128 v[50:53], v54 offset:40256
	ds_read_b128 v[54:57], v54 offset:42880
	ds_read_b128 v[58:61], v62 offset:40256
	ds_read_b128 v[62:65], v62 offset:42880
	s_nop 6
	v_cvt_pk_bf16_f32 v66, v66, v67
	v_mfma_f32_32x32x16_bf16 v[34:49], v[186:189], v[130:133], v[34:49]
	v_cvt_pk_bf16_f32 v67, v68, v69
	v_cvt_pk_bf16_f32 v68, v70, v71
	v_cvt_pk_bf16_f32 v69, v72, v73
	v_cvt_pk_bf16_f32 v70, v74, v75
	v_cvt_pk_bf16_f32 v72, v78, v79
	v_add_u32_e32 v78, 0xc800, v172
	v_lshl_add_u32 v74, v145, 1, v172
	s_waitcnt lgkmcnt(3)
	v_mfma_f32_32x32x16_bf16 v[18:33], v[50:53], v[130:133], v[18:33]
	v_bitop3_b32 v50, v141, 8, 24 bitop3:0x6c
	v_lshl_add_u32 v75, v50, 1, v172
	v_bitop3_b32 v50, v141, 16, 24 bitop3:0x6c
	v_lshl_add_u32 v145, v50, 1, v172
	ds_read2_b64 v[50:53], v78 offset0:248 offset1:250
	v_cvt_pk_bf16_f32 v71, v76, v77
	v_cvt_pk_bf16_f32 v73, v80, v81
	v_mfma_f32_32x32x16_bf16 v[34:49], v[190:193], v[126:129], v[34:49]
	s_waitcnt lgkmcnt(0)
	v_mfma_f32_32x32x16_bf16 v[34:49], v[50:53], v[66:69], v[34:49]
	v_mfma_f32_32x32x16_bf16 v[18:33], v[58:61], v[126:129], v[18:33]
	v_bitop3_b32 v58, v141, 24, v141 bitop3:0xc
	v_lshl_add_u32 v141, v58, 1, v172
	ds_read_b64 v[58:59], v74 offset:35072
	ds_read_b64 v[60:61], v75 offset:35072
	ds_read_b64 v[76:77], v75 offset:37696
	ds_read_b64 v[74:75], v74 offset:37696
	ds_read2_b64 v[78:81], v78 offset0:252 offset1:254
	ds_read_b64 v[50:51], v145 offset:35072
	ds_read_b64 v[52:53], v141 offset:35072
	ds_read_b64 v[174:175], v141 offset:37696
	ds_read_b64 v[172:173], v145 offset:37696
	v_xor_b32_e32 v141, 31, v0
	v_cndmask_b32_e64 v141, v141, v0, s[10:11]
	v_mov_b32_e32 v145, v1
	s_waitcnt lgkmcnt(4)
	v_mfma_f32_32x32x16_bf16 v[34:49], v[78:81], v[70:73], v[34:49]
	v_or_b32_e32 v78, s12, v141
	v_ashrrev_i32_e32 v79, 31, v78
	v_lshl_add_u64 v[144:145], s[56:57], 0, v[144:145]
	v_lshlrev_b64 v[78:79], 12, v[78:79]
	v_lshl_add_u64 v[78:79], v[144:145], 0, v[78:79]
	s_and_b64 vcc, exec, s[10:11]
	s_cbranch_vccnz .Lys_fwd
	s_nop 6
	global_atomic_add_f32 v[78:79], v34, off
	v_xor_b32_e32 v34, 30, v0
	v_cndmask_b32_e64 v34, v34, v143, s[10:11]
	v_mfma_f32_32x32x16_bf16 v[2:17], v[54:57], v[130:133], v[2:17]
	v_or_b32_e32 v54, s12, v34
	v_ashrrev_i32_e32 v55, 31, v54
	v_xor_b32_e32 v34, 29, v0
	v_lshlrev_b64 v[54:55], 12, v[54:55]
	v_cndmask_b32_e64 v34, v34, v158, s[10:11]
	v_lshl_add_u64 v[54:55], v[144:145], 0, v[54:55]
	v_or_b32_e32 v34, s12, v34
	global_atomic_add_f32 v[54:55], v35, off
	v_ashrrev_i32_e32 v35, 31, v34
	v_lshlrev_b64 v[34:35], 12, v[34:35]
	v_lshl_add_u64 v[34:35], v[144:145], 0, v[34:35]
	global_atomic_add_f32 v[34:35], v36, off
	v_xor_b32_e32 v34, 28, v0
	v_cndmask_b32_e64 v34, v34, v159, s[10:11]
	v_or_b32_e32 v34, s12, v34
	v_ashrrev_i32_e32 v35, 31, v34
	v_lshlrev_b64 v[34:35], 12, v[34:35]
	v_lshl_add_u64 v[34:35], v[144:145], 0, v[34:35]
	global_atomic_add_f32 v[34:35], v37, off
	v_xor_b32_e32 v34, 23, v0
	v_cndmask_b32_e64 v34, v34, v160, s[10:11]
	v_or_b32_e32 v34, s12, v34
	v_ashrrev_i32_e32 v35, 31, v34
	v_lshlrev_b64 v[34:35], 12, v[34:35]
	v_lshl_add_u64 v[34:35], v[144:145], 0, v[34:35]
	global_atomic_add_f32 v[34:35], v38, off
	v_xor_b32_e32 v34, 22, v0
	v_cndmask_b32_e64 v34, v34, v161, s[10:11]
	v_or_b32_e32 v34, s12, v34
	v_ashrrev_i32_e32 v35, 31, v34
	v_lshlrev_b64 v[34:35], 12, v[34:35]
	v_lshl_add_u64 v[34:35], v[144:145], 0, v[34:35]
	global_atomic_add_f32 v[34:35], v39, off
	v_xor_b32_e32 v34, 21, v0
	v_cndmask_b32_e64 v34, v34, v162, s[10:11]
	v_or_b32_e32 v34, s12, v34
	v_ashrrev_i32_e32 v35, 31, v34
	v_lshlrev_b64 v[34:35], 12, v[34:35]
	v_lshl_add_u64 v[34:35], v[144:145], 0, v[34:35]
	global_atomic_add_f32 v[34:35], v40, off
	v_xor_b32_e32 v34, 20, v0
	v_cndmask_b32_e64 v34, v34, v163, s[10:11]
	v_or_b32_e32 v34, s12, v34
	v_ashrrev_i32_e32 v35, 31, v34
	v_lshlrev_b64 v[34:35], 12, v[34:35]
	v_lshl_add_u64 v[34:35], v[144:145], 0, v[34:35]
	global_atomic_add_f32 v[34:35], v41, off
	v_xor_b32_e32 v34, 15, v0
	v_cndmask_b32_e64 v34, v34, v164, s[10:11]
	v_or_b32_e32 v34, s12, v34
	v_ashrrev_i32_e32 v35, 31, v34
	v_lshlrev_b64 v[34:35], 12, v[34:35]
	v_lshl_add_u64 v[34:35], v[144:145], 0, v[34:35]
	global_atomic_add_f32 v[34:35], v42, off
	v_xor_b32_e32 v34, 14, v0
	v_cndmask_b32_e64 v34, v34, v165, s[10:11]
	v_or_b32_e32 v34, s12, v34
	v_ashrrev_i32_e32 v35, 31, v34
	v_lshlrev_b64 v[34:35], 12, v[34:35]
	v_lshl_add_u64 v[34:35], v[144:145], 0, v[34:35]
	global_atomic_add_f32 v[34:35], v43, off
	v_xor_b32_e32 v34, 13, v0
	v_cndmask_b32_e64 v34, v34, v166, s[10:11]
	v_or_b32_e32 v34, s12, v34
	v_ashrrev_i32_e32 v35, 31, v34
	v_lshlrev_b64 v[34:35], 12, v[34:35]
	v_lshl_add_u64 v[34:35], v[144:145], 0, v[34:35]
	global_atomic_add_f32 v[34:35], v44, off
	v_xor_b32_e32 v34, 12, v0
	v_cndmask_b32_e64 v34, v34, v167, s[10:11]
	v_or_b32_e32 v34, s12, v34
	v_ashrrev_i32_e32 v35, 31, v34
	v_lshlrev_b64 v[34:35], 12, v[34:35]
	v_lshl_add_u64 v[34:35], v[144:145], 0, v[34:35]
	global_atomic_add_f32 v[34:35], v45, off
	v_xor_b32_e32 v34, 7, v0
	v_cndmask_b32_e64 v34, v34, v168, s[10:11]
	v_or_b32_e32 v34, s12, v34
	v_ashrrev_i32_e32 v35, 31, v34
	v_lshlrev_b64 v[34:35], 12, v[34:35]
	v_lshl_add_u64 v[34:35], v[144:145], 0, v[34:35]
	global_atomic_add_f32 v[34:35], v46, off
	v_xor_b32_e32 v34, 6, v0
	v_cndmask_b32_e64 v34, v34, v169, s[10:11]
	v_or_b32_e32 v34, s12, v34
	v_ashrrev_i32_e32 v35, 31, v34
	v_lshlrev_b64 v[34:35], 12, v[34:35]
	v_lshl_add_u64 v[34:35], v[144:145], 0, v[34:35]
	global_atomic_add_f32 v[34:35], v47, off
	v_xor_b32_e32 v34, 5, v0
	v_cndmask_b32_e64 v34, v34, v170, s[10:11]
	v_or_b32_e32 v34, s12, v34
	v_ashrrev_i32_e32 v35, 31, v34
	v_lshlrev_b64 v[34:35], 12, v[34:35]
	v_xor_b32_e32 v0, 4, v0
	v_lshl_add_u64 v[34:35], v[144:145], 0, v[34:35]
	v_cndmask_b32_e64 v0, v0, v171, s[10:11]
	global_atomic_add_f32 v[34:35], v48, off
	v_or_b32_e32 v34, s12, v0
	v_ashrrev_i32_e32 v35, 31, v34
	v_lshlrev_b64 v[34:35], 12, v[34:35]
	v_lshl_add_u64 v[34:35], v[144:145], 0, v[34:35]
	global_atomic_add_f32 v[34:35], v49, off
	s_branch .Lys_join

.Le23_skip_c:
	s_waitcnt lgkmcnt(0)
	s_barrier
	s_andn2_b64 vcc, exec, s[8:9]
	s_cbranch_vccnz .LBB0_1235
	v_lshlrev_b32_e32 v80, 1, v0
	v_add_u32_e32 v46, v66, v80
	v_add_u32_e32 v47, 0x4000, v46
	ds_read2_b64 v[34:37], v47 offset0:32 offset1:34
	v_cvt_pk_bf16_f32 v38, v18, v19
	v_cvt_pk_bf16_f32 v39, v20, v21
	v_cvt_pk_bf16_f32 v40, v22, v23
	v_cvt_pk_bf16_f32 v41, v24, v25
	ds_read2_b64 v[42:45], v47 offset0:36 offset1:38
	v_lshlrev_b32_e32 v48, 3, v51
	v_cvt_pk_bf16_f32 v72, v26, v27
	v_cvt_pk_bf16_f32 v73, v28, v29
	s_waitcnt lgkmcnt(1)
	v_mfma_f32_32x32x16_bf16 v[50:65], v[34:37], v[38:41], 0
	v_cvt_pk_bf16_f32 v74, v30, v31
	v_cvt_pk_bf16_f32 v75, v32, v33
	ds_read2_b64 v[34:37], v47 offset0:40 offset1:42
	v_cvt_pk_bf16_f32 v76, v2, v3
	v_cvt_pk_bf16_f32 v77, v4, v5
	v_cvt_pk_bf16_f32 v78, v6, v7
	v_cvt_pk_bf16_f32 v79, v8, v9
	s_waitcnt lgkmcnt(1)
	v_mfma_f32_32x32x16_bf16 v[50:65], v[42:45], v[72:75], v[50:65]
	ds_read2_b64 v[42:45], v47 offset0:44 offset1:46
	v_cvt_pk_bf16_f32 v172, v10, v11
	v_cvt_pk_bf16_f32 v173, v12, v13
	v_cvt_pk_bf16_f32 v174, v14, v15
	v_cvt_pk_bf16_f32 v175, v16, v17
	v_mov_b32_e32 v49, s88
	v_bitop3_b32 v47, v48, v141, 24 bitop3:0x78
	s_waitcnt lgkmcnt(1)
	v_mfma_f32_32x32x16_bf16 v[50:65], v[34:37], v[76:79], v[50:65]
	v_lshlrev_b32_e32 v34, 6, v70
	v_sub_u32_e32 v177, v66, v34
	v_lshl_add_u32 v70, v48, 1, v177
	ds_read_b128 v[34:37], v70 offset:50624
	v_mad_u32_u24 v49, v71, s77, v49
	v_lshlrev_b32_e32 v207, 1, v47
	v_and_b32_e32 v145, 24, v141
	s_waitcnt lgkmcnt(1)
	v_mfma_f32_32x32x16_bf16 v[50:65], v[42:45], v[172:175], v[50:65]
	v_add_u32_e32 v42, v49, v207
	ds_read_b128 v[130:133], v42 offset:45440
	v_bitop3_b32 v67, v48, v145, 16 bitop3:0x36
	v_lshlrev_b32_e32 v212, 1, v67
	v_add_u32_e32 v71, 0x5000, v46
	v_add_u32_e32 v47, v49, v212
	ds_read_b128 v[42:45], v70 offset:50656
	ds_read_b128 v[126:129], v47 offset:45440
	s_waitcnt lgkmcnt(2)
	v_mfma_f32_32x32x16_bf16 v[50:65], v[34:37], v[130:133], v[50:65]
	ds_read2_b64 v[34:37], v71 offset0:96 offset1:98
	ds_read2_b64 v[66:69], v71 offset0:100 offset1:102
	ds_read2_b64 v[178:181], v71 offset0:104 offset1:106
	ds_read2_b64 v[182:185], v71 offset0:108 offset1:110
	ds_read_b128 v[186:189], v70 offset:55744
	ds_read_b128 v[190:193], v70 offset:55776
	v_lshlrev_b32_e32 v81, 2, v0
	s_add_i32 s58, s89, 32
	s_and_b64 s[12:13], s[10:11], exec
	s_cselect_b32 s12, s91, s58
	s_waitcnt lgkmcnt(6)
	v_mfma_f32_32x32x16_bf16 v[50:65], v[42:45], v[126:129], v[50:65]
	s_add_i32 s12, s12, s83
	s_waitcnt lgkmcnt(5)
	v_mfma_f32_32x32x16_bf16 v[34:49], v[34:37], v[38:41], 0
	s_nop 8
	v_cvt_pk_bf16_f32 v50, v50, v51
	v_cvt_pk_bf16_f32 v51, v52, v53
	v_cvt_pk_bf16_f32 v52, v54, v55
	v_cvt_pk_bf16_f32 v53, v56, v57
	s_waitcnt lgkmcnt(4)
	v_mfma_f32_32x32x16_bf16 v[34:49], v[66:69], v[72:75], v[34:49]
	ds_read_b128 v[66:69], v81 offset:60928
	ds_read_b128 v[70:73], v81 offset:60960
	ds_read_b128 v[194:197], v81 offset:60864
	ds_read_b128 v[198:201], v81 offset:60896
	ds_read_b128 v[202:205], v81 offset:60992
	ds_read_b128 v[208:211], v81 offset:61024
	s_waitcnt lgkmcnt(4)
	v_pk_mul_f32 v[30:31], v[30:31], v[70:71]
	v_pk_mul_f32 v[26:27], v[26:27], v[66:67]
	v_pk_mul_f32 v[32:33], v[32:33], v[72:73]
	v_pk_mul_f32 v[28:29], v[28:29], v[68:69]
	ds_read_b128 v[66:69], v81 offset:61056
	ds_read_b128 v[70:73], v81 offset:61088
	s_waitcnt lgkmcnt(4)
	v_pk_mul_f32 v[22:23], v[22:23], v[198:199]
	v_mfma_f32_32x32x16_bf16 v[34:49], v[178:181], v[76:79], v[34:49]
	v_mul_f32_e64 v24, v24, v200
	v_mul_f32_e64 v25, v25, v201
	s_waitcnt lgkmcnt(1)
	v_mul_f32_e64 v10, v10, v66
	v_mul_f32_e64 v11, v11, v67
	s_waitcnt lgkmcnt(0)
	v_pk_mul_f32 v[14:15], v[14:15], v[70:71]
	v_pk_mul_f32 v[16:17], v[16:17], v[72:73]
	v_pk_mul_f32 v[12:13], v[12:13], v[68:69]
	v_pk_mul_f32 v[20:21], v[20:21], v[196:197]
	v_pk_mul_f32 v[18:19], v[18:19], v[194:195]
	v_mfma_f32_32x32x16_bf16 v[34:49], v[182:185], v[172:175], v[34:49]
	v_add_u32_e32 v172, v177, v80
	v_add_u32_e32 v66, 0xe000, v172
	ds_read2_b64 v[74:77], v66 offset0:120 offset1:122
	ds_read2_b64 v[54:57], v66 offset0:124 offset1:126
	v_mul_f32_e64 v6, v6, v208
	v_mul_f32_e64 v7, v7, v209
	v_pk_mul_f32 v[8:9], v[8:9], v[210:211]
	v_pk_mul_f32 v[4:5], v[4:5], v[204:205]
	s_waitcnt lgkmcnt(1)
	v_mfma_f32_32x32x16_bf16 v[66:81], v[74:77], v[50:53], 0
	v_cvt_pk_bf16_f32 v50, v58, v59
	v_cvt_pk_bf16_f32 v51, v60, v61
	v_cvt_pk_bf16_f32 v52, v62, v63
	v_cvt_pk_bf16_f32 v53, v64, v65
	v_add_u32_e32 v62, v177, v212
	v_pk_mul_f32 v[2:3], v[2:3], v[202:203]
	s_waitcnt lgkmcnt(0)
	v_mfma_f32_32x32x16_bf16 v[66:81], v[54:57], v[50:53], v[66:81]
	v_add_u32_e32 v54, v177, v207
	ds_read_b128 v[50:53], v54 offset:40256
	ds_read_b128 v[54:57], v54 offset:42880
	ds_read_b128 v[58:61], v62 offset:40256
	ds_read_b128 v[62:65], v62 offset:42880
	s_nop 6
	v_cvt_pk_bf16_f32 v66, v66, v67
	v_mfma_f32_32x32x16_bf16 v[34:49], v[186:189], v[130:133], v[34:49]
	v_cvt_pk_bf16_f32 v67, v68, v69
	v_cvt_pk_bf16_f32 v68, v70, v71
	v_cvt_pk_bf16_f32 v69, v72, v73
	v_cvt_pk_bf16_f32 v70, v74, v75
	v_cvt_pk_bf16_f32 v72, v78, v79
	v_add_u32_e32 v78, 0xc800, v172
	v_lshl_add_u32 v74, v145, 1, v172
	s_waitcnt lgkmcnt(3)
	v_mfma_f32_32x32x16_bf16 v[18:33], v[50:53], v[130:133], v[18:33]
	v_bitop3_b32 v50, v141, 8, 24 bitop3:0x6c
	v_lshl_add_u32 v75, v50, 1, v172
	v_bitop3_b32 v50, v141, 16, 24 bitop3:0x6c
	v_lshl_add_u32 v145, v50, 1, v172
	ds_read2_b64 v[50:53], v78 offset0:248 offset1:250
	v_cvt_pk_bf16_f32 v71, v76, v77
	v_cvt_pk_bf16_f32 v73, v80, v81
	v_mfma_f32_32x32x16_bf16 v[34:49], v[190:193], v[126:129], v[34:49]
	s_waitcnt lgkmcnt(0)
	v_mfma_f32_32x32x16_bf16 v[34:49], v[50:53], v[66:69], v[34:49]
	v_mfma_f32_32x32x16_bf16 v[18:33], v[58:61], v[126:129], v[18:33]
	v_bitop3_b32 v58, v141, 24, v141 bitop3:0xc
	v_lshl_add_u32 v141, v58, 1, v172
	ds_read_b64 v[58:59], v74 offset:35072
	ds_read_b64 v[60:61], v75 offset:35072
	ds_read_b64 v[76:77], v75 offset:37696
	ds_read_b64 v[74:75], v74 offset:37696
	ds_read2_b64 v[78:81], v78 offset0:252 offset1:254
	ds_read_b64 v[50:51], v145 offset:35072
	ds_read_b64 v[52:53], v141 offset:35072
	ds_read_b64 v[174:175], v141 offset:37696
	ds_read_b64 v[172:173], v145 offset:37696
	v_xor_b32_e32 v141, 31, v0
	v_cndmask_b32_e64 v141, v141, v0, s[10:11]
	v_or_b32_e32 v178, s12, v141
	s_waitcnt lgkmcnt(4)
	v_mfma_f32_32x32x16_bf16 v[34:49], v[78:81], v[70:73], v[34:49]
	v_mov_b32_e32 v145, v1
	v_ashrrev_i32_e32 v179, 31, v178
	v_lshl_add_u64 v[144:145], s[56:57], 0, v[144:145]
	v_lshlrev_b64 v[78:79], 12, v[178:179]
	v_lshl_add_u64 v[78:79], v[144:145], 0, v[78:79]
	s_nop 6
	global_atomic_add_f32 v[78:79], v34, off
	v_xor_b32_e32 v34, 30, v0
	v_cndmask_b32_e64 v34, v34, v143, s[10:11]
	v_or_b32_e32 v78, s12, v34
	v_ashrrev_i32_e32 v79, 31, v78
	v_xor_b32_e32 v34, 29, v0
	v_mfma_f32_32x32x16_bf16 v[2:17], v[54:57], v[130:133], v[2:17]
	v_lshlrev_b64 v[54:55], 12, v[78:79]
	v_cndmask_b32_e64 v34, v34, v158, s[10:11]
	v_lshl_add_u64 v[54:55], v[144:145], 0, v[54:55]
	v_or_b32_e32 v34, s12, v34
	global_atomic_add_f32 v[54:55], v35, off
	v_ashrrev_i32_e32 v35, 31, v34
	v_lshlrev_b64 v[34:35], 12, v[34:35]
	v_lshl_add_u64 v[34:35], v[144:145], 0, v[34:35]
	global_atomic_add_f32 v[34:35], v36, off
	v_xor_b32_e32 v34, 28, v0
	v_cndmask_b32_e64 v34, v34, v159, s[10:11]
	v_or_b32_e32 v34, s12, v34
	v_ashrrev_i32_e32 v35, 31, v34
	v_lshlrev_b64 v[34:35], 12, v[34:35]
	v_lshl_add_u64 v[34:35], v[144:145], 0, v[34:35]
	global_atomic_add_f32 v[34:35], v37, off
	v_xor_b32_e32 v34, 23, v0
	v_cndmask_b32_e64 v34, v34, v160, s[10:11]
	v_or_b32_e32 v34, s12, v34
	v_ashrrev_i32_e32 v35, 31, v34
	v_lshlrev_b64 v[34:35], 12, v[34:35]
	v_lshl_add_u64 v[34:35], v[144:145], 0, v[34:35]
	global_atomic_add_f32 v[34:35], v38, off
	v_xor_b32_e32 v34, 22, v0
	v_cndmask_b32_e64 v34, v34, v161, s[10:11]
	v_or_b32_e32 v34, s12, v34
	v_ashrrev_i32_e32 v35, 31, v34
	v_lshlrev_b64 v[34:35], 12, v[34:35]
	v_lshl_add_u64 v[34:35], v[144:145], 0, v[34:35]
	global_atomic_add_f32 v[34:35], v39, off
	v_xor_b32_e32 v34, 21, v0
	v_cndmask_b32_e64 v34, v34, v162, s[10:11]
	v_or_b32_e32 v34, s12, v34
	v_ashrrev_i32_e32 v35, 31, v34
	v_lshlrev_b64 v[34:35], 12, v[34:35]
	v_lshl_add_u64 v[34:35], v[144:145], 0, v[34:35]
	global_atomic_add_f32 v[34:35], v40, off
	v_xor_b32_e32 v34, 20, v0
	v_cndmask_b32_e64 v34, v34, v163, s[10:11]
	v_or_b32_e32 v34, s12, v34
	v_ashrrev_i32_e32 v35, 31, v34
	v_lshlrev_b64 v[34:35], 12, v[34:35]
	v_lshl_add_u64 v[34:35], v[144:145], 0, v[34:35]
	global_atomic_add_f32 v[34:35], v41, off
	v_xor_b32_e32 v34, 15, v0
	v_cndmask_b32_e64 v34, v34, v164, s[10:11]
	v_or_b32_e32 v34, s12, v34
	v_ashrrev_i32_e32 v35, 31, v34
	v_lshlrev_b64 v[34:35], 12, v[34:35]
	v_lshl_add_u64 v[34:35], v[144:145], 0, v[34:35]
	global_atomic_add_f32 v[34:35], v42, off
	v_xor_b32_e32 v34, 14, v0
	v_cndmask_b32_e64 v34, v34, v165, s[10:11]
	v_or_b32_e32 v34, s12, v34
	v_ashrrev_i32_e32 v35, 31, v34
	v_lshlrev_b64 v[34:35], 12, v[34:35]
	v_lshl_add_u64 v[34:35], v[144:145], 0, v[34:35]
	global_atomic_add_f32 v[34:35], v43, off
	v_xor_b32_e32 v34, 13, v0
	v_cndmask_b32_e64 v34, v34, v166, s[10:11]
	v_or_b32_e32 v34, s12, v34
	v_ashrrev_i32_e32 v35, 31, v34
	v_lshlrev_b64 v[34:35], 12, v[34:35]
	v_lshl_add_u64 v[34:35], v[144:145], 0, v[34:35]
	global_atomic_add_f32 v[34:35], v44, off
	v_xor_b32_e32 v34, 12, v0
	v_cndmask_b32_e64 v34, v34, v167, s[10:11]
	v_or_b32_e32 v34, s12, v34
	v_ashrrev_i32_e32 v35, 31, v34
	v_lshlrev_b64 v[34:35], 12, v[34:35]
	v_lshl_add_u64 v[34:35], v[144:145], 0, v[34:35]
	global_atomic_add_f32 v[34:35], v45, off
	v_xor_b32_e32 v34, 7, v0
	v_cndmask_b32_e64 v34, v34, v168, s[10:11]
	v_or_b32_e32 v34, s12, v34
	v_ashrrev_i32_e32 v35, 31, v34
	v_lshlrev_b64 v[34:35], 12, v[34:35]
	v_lshl_add_u64 v[34:35], v[144:145], 0, v[34:35]
	global_atomic_add_f32 v[34:35], v46, off
	v_xor_b32_e32 v34, 6, v0
	v_cndmask_b32_e64 v34, v34, v169, s[10:11]
	v_or_b32_e32 v34, s12, v34
	v_ashrrev_i32_e32 v35, 31, v34
	v_lshlrev_b64 v[34:35], 12, v[34:35]
	v_lshl_add_u64 v[34:35], v[144:145], 0, v[34:35]
	global_atomic_add_f32 v[34:35], v47, off
	v_xor_b32_e32 v34, 5, v0
	v_cndmask_b32_e64 v34, v34, v170, s[10:11]
	v_or_b32_e32 v34, s12, v34
	v_ashrrev_i32_e32 v35, 31, v34
	v_lshlrev_b64 v[34:35], 12, v[34:35]
	v_xor_b32_e32 v0, 4, v0
	v_lshl_add_u64 v[34:35], v[144:145], 0, v[34:35]
	v_cndmask_b32_e64 v0, v0, v171, s[10:11]
	global_atomic_add_f32 v[34:35], v48, off
	v_or_b32_e32 v34, s12, v0
	v_ashrrev_i32_e32 v35, 31, v34
	v_lshlrev_b64 v[34:35], 12, v[34:35]
	v_lshl_add_u64 v[34:35], v[144:145], 0, v[34:35]
	global_atomic_add_f32 v[34:35], v49, off
	v_mfma_f32_32x32x16_bf16 v[2:17], v[62:65], v[126:129], v[2:17]
	v_mfma_f32_32x32x16_bf16 v[18:33], v[58:61], v[66:69], v[18:33]
	v_mfma_f32_32x32x16_bf16 v[2:17], v[74:77], v[66:69], v[2:17]
	s_waitcnt lgkmcnt(2)
	v_mfma_f32_32x32x16_bf16 v[18:33], v[50:53], v[70:73], v[18:33]
	s_waitcnt lgkmcnt(0)
	v_mfma_f32_32x32x16_bf16 v[2:17], v[172:175], v[70:73], v[2:17]
	s_branch .LBB0_1235
